# v53 + in-proj layer-0 32-unit groups permuted across XCDs (2 K0 groups + 1 T group per XCD), leftover units untouched
# speedup vs baseline: 1.0015x; 1.0015x over previous
;     __device__ __forceinline__ bool next(int i, Unit& u) const {
;         int q, hf; if (!L.idx(i, q, hf)) return false;
;         const char* H = (const char*)(ws + OFF_HY);
;         u.p1 = nullptr; u.p2 = nullptr; u.nt = 16; u.mode = 0; u.half = 0; u.mk = -1; u.mneg = 0;
;         int kind, pm, pn, bt = 0;
;         if (!l1) { if (q < 504) { kind = 0; const int gid = q / 56, rem = q % 56; pm = gid * 8 + (rem & 7); pn = rem >> 3; } else if (q < 760) { const int s = q - 504; kind = 1; bt = s >> 5; pn = (s & 31) >> 2; pm = s & 3; } else { const int s = q - 760; kind = 2; bt = s >> 2; pm = s & 3; pn = 0; } }
.LBB0_387:
	s_andn2_b64 vcc, exec, s[4:5]
	s_cbranch_vccnz .LBB0_395
	s_mul_hi_u32 s18, s19, 0x295fad5
	s_mul_i32 s20, s18, 0x63
	s_sub_i32 s20, s19, s20
	s_cmpk_gt_u32 s20, 0x5f
	s_cbranch_scc1 .Lperm0_skip_a
	s_lshr_b32 s22, s20, 5
	s_and_b32 s20, s20, 31
	s_cmp_lt_u32 s18, 7
	s_cbranch_scc0 .Lperm0_hi_a
	s_lshl_b32 s23, s18, 1
	s_add_i32 s23, s23, s22
	s_add_i32 s18, s18, 15
	s_cmp_lt_u32 s22, 2
	s_cselect_b32 s23, s23, s18
	s_branch .Lperm0_done_a
.Lperm0_hi_a:
	s_add_i32 s23, s22, 21
	s_cmp_eq_u32 s22, 0
	s_cselect_b32 s23, 14, s23
.Lperm0_done_a:
	s_mul_i32 s18, s23, 11
	s_lshr_b32 s18, s18, 5
	s_mul_i32 s22, s18, 3
	s_sub_i32 s22, s23, s22
	s_mul_i32 s18, s18, 0x63
	s_lshl_b32 s22, s22, 5
	s_add_i32 s19, s18, s22
	s_add_i32 s19, s19, s20
.Lperm0_skip_a:
	s_cmpk_gt_i32 s19, 0x1f7
	s_mov_b64 s[4:5], -1
	s_cbranch_scc0 .LBB0_393
	s_cmpk_gt_u32 s19, 0x2f7
	s_mov_b64 s[10:11], -1
	s_cbranch_scc0 .LBB0_391
	s_add_i32 s3, s19, 0xfffffd08
	s_lshr_b32 s56, s3, 2
	s_and_b32 s18, s19, 3
	s_mov_b64 s[10:11], 0

;     __device__ __forceinline__ bool next(int i, Unit& u) const {
;         int q, hf; if (!L.idx(i, q, hf)) return false;
;         const char* H = (const char*)(ws + OFF_HY);
;         u.p1 = nullptr; u.p2 = nullptr; u.nt = 16; u.mode = 0; u.half = 0; u.mk = -1; u.mneg = 0;
;         int kind, pm, pn, bt = 0;
;         if (!l1) { if (q < 504) { kind = 0; const int gid = q / 56, rem = q % 56; pm = gid * 8 + (rem & 7); pn = rem >> 3; } else if (q < 760) { const int s = q - 504; kind = 1; bt = s >> 5; pn = (s & 31) >> 2; pm = s & 3; } else { const int s = q - 760; kind = 2; bt = s >> 2; pm = s & 3; pn = 0; } }
.LBB0_428:
	s_andn2_b64 vcc, exec, s[4:5]
	s_cbranch_vccnz .LBB0_436
	s_mul_hi_u32 s8, s9, 0x295fad5
	s_mul_i32 s28, s8, 0x63
	s_sub_i32 s28, s9, s28
	s_cmpk_gt_u32 s28, 0x5f
	s_cbranch_scc1 .Lperm0_skip_b
	s_lshr_b32 s38, s28, 5
	s_and_b32 s28, s28, 31
	s_cmp_lt_u32 s8, 7
	s_cbranch_scc0 .Lperm0_hi_b
	s_lshl_b32 s39, s8, 1
	s_add_i32 s39, s39, s38
	s_add_i32 s8, s8, 15
	s_cmp_lt_u32 s38, 2
	s_cselect_b32 s39, s39, s8
	s_branch .Lperm0_done_b
.Lperm0_hi_b:
	s_add_i32 s39, s38, 21
	s_cmp_eq_u32 s38, 0
	s_cselect_b32 s39, 14, s39
.Lperm0_done_b:
	s_mul_i32 s8, s39, 11
	s_lshr_b32 s8, s8, 5
	s_mul_i32 s38, s8, 3
	s_sub_i32 s38, s39, s38
	s_mul_i32 s8, s8, 0x63
	s_lshl_b32 s38, s38, 5
	s_add_i32 s9, s8, s38
	s_add_i32 s9, s9, s28
.Lperm0_skip_b:
	s_cmpk_gt_i32 s9, 0x1f7
	s_mov_b64 s[4:5], -1
	s_cbranch_scc0 .LBB0_434
	s_cmpk_gt_u32 s9, 0x2f7
	s_mov_b64 s[28:29], -1
	s_cbranch_scc0 .LBB0_432
	s_add_i32 s4, s9, 0xfffffd08
	s_lshr_b32 s56, s4, 2
	s_and_b32 s8, s9, 3
	s_mov_b64 s[28:29], 0
